# NSA top-k threshold search: pipelined compare/add-carry counting and DPP quad reduction instead of LDS permutes
# speedup vs baseline: 1.0043x; 1.0043x over previous
; __device__ __forceinline__ void nsa_unit(LAS unsigned char* lds, const Ctx& X, bf16_t* OB, int b, int g, int qb) {
;     ...
;     unsigned thr = 0u;
; #pragma unroll 1
;     ...
;       const unsigned cand = thr | (1u << bit); int cn = 0;
; #pragma unroll
;       for (int jj = 0; jj < 32; ++jj) cn += (sj[jj] >= cand) ? 1 : 0;
;       cn += __shfl_xor(cn, 1); cn += __shfl_xor(cn, 2);
;       thr = (cn >= 16) ? cand : thr;
;     }
;     int mine = 0;
; #pragma unroll
;     for (int jj = 0; jj < 32; ++jj) mine += (sj[jj] >= thr) ? 1 : 0;
;     const int c0 = __shfl(mine, (lane & ~3) + 0), c1 = __shfl(mine, (lane & ~3) + 1), c2 = __shfl(mine, (lane & ~3) + 2);
;     int slot = (part > 0 ? c0 : 0) + (part > 1 ? c1 : 0) + (part > 2 ? c2 : 0);
.LBB0_1149:
	s_lshl_b32 s9, 1, s8
	v_or_b32_e32 v39, s9, v1
	s_waitcnt lgkmcnt(0)
	s_add_i32 s8, s8, -1
	v_mov_b32_e32 v40, 0
	s_cmp_eq_u32 s8, -1
	v_cmp_ge_u32_e64 s[10:11], v31, v39
	v_cmp_ge_u32_e64 s[12:13], v30, v39
	v_cmp_ge_u32_e32 vcc, v32, v39
	v_addc_co_u32_e64 v40, s[10:11], 0, v40, s[10:11]
	v_cmp_ge_u32_e64 s[10:11], v33, v39
	v_addc_co_u32_e64 v40, s[12:13], 0, v40, s[12:13]
	v_cmp_ge_u32_e64 s[12:13], v26, v39
	v_addc_co_u32_e32 v40, vcc, 0, v40, vcc
	v_cmp_ge_u32_e32 vcc, v27, v39
	v_addc_co_u32_e64 v40, s[10:11], 0, v40, s[10:11]
	v_cmp_ge_u32_e64 s[10:11], v28, v39
	v_addc_co_u32_e64 v40, s[12:13], 0, v40, s[12:13]
	v_cmp_ge_u32_e64 s[12:13], v29, v39
	v_addc_co_u32_e32 v40, vcc, 0, v40, vcc
	v_cmp_ge_u32_e32 vcc, v22, v39
	v_addc_co_u32_e64 v40, s[10:11], 0, v40, s[10:11]
	v_cmp_ge_u32_e64 s[10:11], v23, v39
	v_addc_co_u32_e64 v40, s[12:13], 0, v40, s[12:13]
	v_cmp_ge_u32_e64 s[12:13], v24, v39
	v_addc_co_u32_e32 v40, vcc, 0, v40, vcc
	v_cmp_ge_u32_e32 vcc, v25, v39
	v_addc_co_u32_e64 v40, s[10:11], 0, v40, s[10:11]
	v_cmp_ge_u32_e64 s[10:11], v18, v39
	v_addc_co_u32_e64 v40, s[12:13], 0, v40, s[12:13]
	v_cmp_ge_u32_e64 s[12:13], v19, v39
	v_addc_co_u32_e32 v40, vcc, 0, v40, vcc
	v_cmp_ge_u32_e32 vcc, v20, v39
	v_addc_co_u32_e64 v40, s[10:11], 0, v40, s[10:11]
	v_cmp_ge_u32_e64 s[10:11], v21, v39
	v_addc_co_u32_e64 v40, s[12:13], 0, v40, s[12:13]
	v_cmp_ge_u32_e64 s[12:13], v14, v39
	v_addc_co_u32_e32 v40, vcc, 0, v40, vcc
	v_cmp_ge_u32_e32 vcc, v15, v39
	v_addc_co_u32_e64 v40, s[10:11], 0, v40, s[10:11]
	v_cmp_ge_u32_e64 s[10:11], v16, v39
	v_addc_co_u32_e64 v40, s[12:13], 0, v40, s[12:13]
	v_cmp_ge_u32_e64 s[12:13], v17, v39
	v_addc_co_u32_e32 v40, vcc, 0, v40, vcc
	v_cmp_ge_u32_e32 vcc, v10, v39
	v_addc_co_u32_e64 v40, s[10:11], 0, v40, s[10:11]
	v_cmp_ge_u32_e64 s[10:11], v11, v39
	v_addc_co_u32_e64 v40, s[12:13], 0, v40, s[12:13]
	v_cmp_ge_u32_e64 s[12:13], v12, v39
	v_addc_co_u32_e32 v40, vcc, 0, v40, vcc
	v_cmp_ge_u32_e32 vcc, v13, v39
	v_addc_co_u32_e64 v40, s[10:11], 0, v40, s[10:11]
	v_cmp_ge_u32_e64 s[10:11], v6, v39
	v_addc_co_u32_e64 v40, s[12:13], 0, v40, s[12:13]
	v_cmp_ge_u32_e64 s[12:13], v7, v39
	v_addc_co_u32_e32 v40, vcc, 0, v40, vcc
	v_cmp_ge_u32_e32 vcc, v8, v39
	v_addc_co_u32_e64 v40, s[10:11], 0, v40, s[10:11]
	v_cmp_ge_u32_e64 s[10:11], v9, v39
	v_addc_co_u32_e64 v40, s[12:13], 0, v40, s[12:13]
	v_cmp_ge_u32_e64 s[12:13], v2, v39
	v_addc_co_u32_e32 v40, vcc, 0, v40, vcc
	v_cmp_ge_u32_e32 vcc, v3, v39
	v_addc_co_u32_e64 v40, s[10:11], 0, v40, s[10:11]
	v_cmp_ge_u32_e64 s[10:11], v4, v39
	v_addc_co_u32_e64 v40, s[12:13], 0, v40, s[12:13]
	v_cmp_ge_u32_e64 s[12:13], v5, v39
	v_addc_co_u32_e32 v40, vcc, 0, v40, vcc
	v_addc_co_u32_e64 v40, s[10:11], 0, v40, s[10:11]
	v_addc_co_u32_e64 v40, s[12:13], 0, v40, s[12:13]
	s_nop 1
	v_add_u32_dpp v40, v40, v40 quad_perm:[1,0,3,2] row_mask:0xf bank_mask:0xf
	s_nop 1
	v_add_u32_dpp v40, v40, v40 quad_perm:[2,3,0,1] row_mask:0xf bank_mask:0xf
	v_cmp_lt_i32_e32 vcc, 15, v40
	s_nop 1
	v_cndmask_b32_e32 v1, v1, v39, vcc
	s_cbranch_scc0 .LBB0_1149
	v_cmp_ge_u32_e32 vcc, v31, v1
	v_and_or_b32 v34, v188, 60, v34
	v_lshlrev_b32_e32 v34, 2, v34
	v_cndmask_b32_e64 v37, 0, 1, vcc
	v_cmp_ge_u32_e32 vcc, v30, v1
	v_or_b32_e32 v39, 4, v34
	s_ashr_i32 s8, s71, 31
	v_addc_co_u32_e64 v37, s[10:11], 0, v37, vcc
	v_cmp_ge_u32_e64 s[10:11], v32, v1
	s_add_u32 s9, s71, s40
	s_addc_u32 s8, s8, 0
	v_cndmask_b32_e64 v38, 0, 1, s[10:11]
	v_cmp_ge_u32_e64 s[10:11], v33, v1
	v_or_b32_e32 v36, s9, v36
	s_mov_b32 s9, s41
	v_addc_co_u32_e64 v37, s[10:11], v37, v38, s[10:11]
	v_cmp_ge_u32_e64 s[10:11], v26, v1
	s_nop 1
	v_cndmask_b32_e64 v38, 0, 1, s[10:11]
	v_cmp_ge_u32_e64 s[10:11], v27, v1
	s_nop 1
	v_addc_co_u32_e64 v37, s[10:11], v37, v38, s[10:11]
	v_cmp_ge_u32_e64 s[10:11], v28, v1
	s_nop 1
	v_cndmask_b32_e64 v38, 0, 1, s[10:11]
	v_cmp_ge_u32_e64 s[10:11], v29, v1
	s_nop 1
	v_addc_co_u32_e64 v37, s[10:11], v37, v38, s[10:11]
	v_cmp_ge_u32_e64 s[10:11], v22, v1
	s_nop 1
	v_cndmask_b32_e64 v38, 0, 1, s[10:11]
	v_cmp_ge_u32_e64 s[10:11], v23, v1
	s_nop 1
	v_addc_co_u32_e64 v37, s[10:11], v37, v38, s[10:11]
	v_cmp_ge_u32_e64 s[10:11], v24, v1
	s_nop 1
	v_cndmask_b32_e64 v38, 0, 1, s[10:11]
	v_cmp_ge_u32_e64 s[10:11], v25, v1
	s_nop 1
	v_addc_co_u32_e64 v37, s[10:11], v37, v38, s[10:11]
	v_cmp_ge_u32_e64 s[10:11], v18, v1
	s_nop 1
	v_cndmask_b32_e64 v38, 0, 1, s[10:11]
	v_cmp_ge_u32_e64 s[10:11], v19, v1
	s_nop 1
	v_addc_co_u32_e64 v37, s[10:11], v37, v38, s[10:11]
	v_cmp_ge_u32_e64 s[10:11], v20, v1
	s_nop 1
	v_cndmask_b32_e64 v38, 0, 1, s[10:11]
	v_cmp_ge_u32_e64 s[10:11], v21, v1
	s_nop 1
	v_addc_co_u32_e64 v37, s[10:11], v37, v38, s[10:11]
	v_cmp_ge_u32_e64 s[10:11], v14, v1
	s_nop 1
	v_cndmask_b32_e64 v38, 0, 1, s[10:11]
	v_cmp_ge_u32_e64 s[10:11], v15, v1
	s_nop 1
	v_addc_co_u32_e64 v37, s[10:11], v37, v38, s[10:11]
	v_cmp_ge_u32_e64 s[10:11], v16, v1
	s_nop 1
	v_cndmask_b32_e64 v38, 0, 1, s[10:11]
	v_cmp_ge_u32_e64 s[10:11], v17, v1
	s_nop 1
	v_addc_co_u32_e64 v37, s[10:11], v37, v38, s[10:11]
	v_cmp_ge_u32_e64 s[10:11], v10, v1
	s_nop 1
	v_cndmask_b32_e64 v38, 0, 1, s[10:11]
	v_cmp_ge_u32_e64 s[10:11], v11, v1
	s_nop 1
	v_addc_co_u32_e64 v37, s[10:11], v37, v38, s[10:11]
	v_cmp_ge_u32_e64 s[10:11], v12, v1
	s_nop 1
	v_cndmask_b32_e64 v38, 0, 1, s[10:11]
	v_cmp_ge_u32_e64 s[10:11], v13, v1
	s_nop 1
	v_addc_co_u32_e64 v37, s[10:11], v37, v38, s[10:11]
	v_cmp_ge_u32_e64 s[10:11], v6, v1
	s_nop 1
	v_cndmask_b32_e64 v38, 0, 1, s[10:11]
	v_cmp_ge_u32_e64 s[10:11], v7, v1
	s_nop 1
	v_addc_co_u32_e64 v37, s[10:11], v37, v38, s[10:11]
	v_cmp_ge_u32_e64 s[10:11], v8, v1
	s_nop 1
	v_cndmask_b32_e64 v38, 0, 1, s[10:11]
	v_cmp_ge_u32_e64 s[10:11], v9, v1
	s_nop 1
	v_addc_co_u32_e64 v37, s[10:11], v37, v38, s[10:11]
	v_cmp_ge_u32_e64 s[10:11], v2, v1
	s_nop 1
	v_cndmask_b32_e64 v38, 0, 1, s[10:11]
	v_cmp_ge_u32_e64 s[10:11], v3, v1
	s_nop 1
	v_addc_co_u32_e64 v37, s[10:11], v37, v38, s[10:11]
	v_cmp_ge_u32_e64 s[10:11], v4, v1
	s_nop 1
	v_cndmask_b32_e64 v38, 0, 1, s[10:11]
	v_cmp_ge_u32_e64 s[10:11], v5, v1
	s_nop 1
	v_addc_co_u32_e64 v37, s[10:11], v37, v38, s[10:11]
	ds_bpermute_b32 v38, v34, v37
	ds_bpermute_b32 v39, v39, v37
	v_or_b32_e32 v34, 8, v34
	ds_bpermute_b32 v34, v34, v37
	v_cmp_ne_u32_e64 s[10:11], 0, v35
	s_waitcnt lgkmcnt(2)
	s_nop 0
	v_cndmask_b32_e64 v37, 0, v38, s[10:11]
	v_cmp_lt_u32_e64 s[10:11], 1, v35
	s_waitcnt lgkmcnt(1)
	s_nop 0
	v_cndmask_b32_e64 v38, 0, v39, s[10:11]
	v_cmp_eq_u32_e64 s[10:11], 3, v35
	s_waitcnt lgkmcnt(0)
	s_nop 0
	v_cndmask_b32_e64 v34, 0, v34, s[10:11]
	v_add3_u32 v34, v38, v37, v34
	v_mov_b32_e32 v37, s8
	v_lshlrev_b64 v[36:37], 5, v[36:37]
	s_lshl_b32 s8, s24, 4
	v_lshl_add_u64 v[36:37], s[16:17], 0, v[36:37]
	v_lshl_add_u64 v[36:37], v[36:37], 0, s[8:9]
	v_lshlrev_b32_e32 v38, 5, v35
	s_and_saveexec_b64 s[10:11], vcc
	s_cbranch_execnz .LBB0_1208
	s_or_b64 exec, exec, s[10:11]
	v_cmp_ge_u32_e32 vcc, v31, v1
	s_and_saveexec_b64 s[10:11], vcc
	s_cbranch_execnz .LBB0_1209
